# trailing wave half of the 8-phase GEMMs at static priority 2
# baseline (speedup 1.0000x reference)
.LBB0_147:
	s_or_b64 exec, exec, s[4:5]
	s_bitcmp1_b32 s95, 0
	s_cselect_b32 s0, 0x15a0000, 0
	v_writelane_b32 v255, s0, 1
	v_readlane_b32 s4, v254, 5
	v_readlane_b32 s0, v254, 7
	v_readlane_b32 s5, v254, 6
	v_mov_b32_e32 v8, v226
	v_readlane_b32 s1, v254, 8
	s_waitcnt lgkmcnt(0)
	s_barrier
	s_and_b64 vcc, exec, s[0:1]
	v_readfirstlane_b32 s22, v8
	s_cbranch_vccz .LBB0_159
	v_lshlrev_b32_e32 v0, 4, v8
	v_add_u32_e32 v1, 0x2000, v0
	v_ashrrev_i32_e32 v2, 31, v1
	v_lshrrev_b32_e32 v2, 22, v2
	v_add_u32_e32 v2, v1, v2
	v_ashrrev_i32_e32 v9, 10, v2
	v_mul_i32_i24_e32 v2, 0x400, v9
	v_sub_u32_e32 v1, v1, v2
	s_load_dwordx2 s[4:5], s[4:5], 0xc0
	v_lshrrev_b32_e32 v2, 4, v1
	v_bitop3_b32 v1, v2, v1, 32 bitop3:0x6c
	v_ashrrev_i32_e32 v2, 31, v1
	v_lshrrev_b32_e32 v2, 26, v2
	v_add_u32_e32 v2, v1, v2
	v_lshlrev_b32_e32 v3, 3, v9
	s_waitcnt lgkmcnt(0)
	s_add_u32 s23, s4, 0x16bf0000
	v_ashrrev_i32_e32 v10, 6, v2
	v_and_b32_e32 v3, -16, v3
	s_addc_u32 s24, s5, 0
	v_readlane_b32 s0, v255, 1
	v_add_u32_e32 v3, v10, v3
	s_add_u32 s25, s4, s0
	v_and_b32_e32 v4, 3, v10
	s_mov_b32 s0, 0x1fffe0
	v_lshrrev_b32_e32 v5, 2, v3
	v_lshlrev_b32_e32 v6, 1, v3
	v_and_b32_e32 v2, 0xc0, v2
	v_and_or_b32 v4, v3, s0, v4
	v_and_b32_e32 v5, 4, v5
	v_and_b32_e32 v6, 24, v6
	v_sub_u32_e32 v1, v1, v2
	v_or3_b32 v4, v4, v5, v6
	v_lshlrev_b32_e32 v5, 5, v9
	v_ashrrev_i16_sdwa v1, v230, sext(v1) dst_sel:DWORD dst_unused:UNUSED_PAD src0_sel:DWORD src1_sel:BYTE_0
	v_and_b32_e32 v5, 32, v5
	v_bfe_i32 v11, v1, 0, 16
	v_add_lshl_u32 v1, v5, v11, 1
	v_lshl_add_u32 v128, v4, 11, v1
	v_lshl_add_u32 v130, v3, 11, v1
	v_bfe_i32 v1, v8, 27, 1
	v_lshrrev_b32_e32 v1, 22, v1
	v_add_u32_e32 v1, v0, v1
	v_and_b32_e32 v1, 0xfffffc00, v1
	v_sub_u32_e32 v0, v0, v1
	v_lshrrev_b32_e32 v1, 4, v0
	v_bitop3_b32 v1, v1, v0, 32 bitop3:0x6c
	v_ashrrev_i32_e32 v0, 31, v0
	v_lshrrev_b32_e32 v0, 26, v0
	v_add_u32_e32 v0, v1, v0
	v_ashrrev_i32_e32 v12, 6, v0
	v_ashrrev_i32_e32 v0, 31, v8
	v_lshrrev_b32_e32 v0, 26, v0
	v_add_u32_e32 v0, v8, v0
	v_ashrrev_i32_e32 v13, 6, v0
	v_lshlrev_b32_e32 v0, 3, v13
	v_and_b32_e32 v0, -16, v0
	v_add_u32_e32 v0, v12, v0
	v_and_b32_e32 v2, 3, v12
	v_lshrrev_b32_e32 v3, 2, v0
	v_lshlrev_b32_e32 v4, 1, v0
	v_and_or_b32 v2, v0, s0, v2
	v_and_b32_e32 v3, 4, v3
	v_and_b32_e32 v4, 24, v4
	v_or3_b32 v2, v2, v3, v4
	v_mul_i32_i24_e32 v4, 64, v12
	s_addc_u32 s26, s5, 0
	s_ashr_i32 s9, s22, 6
	v_sub_u32_e32 v1, v1, v4
	s_ashr_i32 s8, s22, 8
	s_lshl_b32 s27, s9, 10
	v_lshlrev_b32_e32 v3, 5, v13
	v_ashrrev_i16_sdwa v1, v230, sext(v1) dst_sel:DWORD dst_unused:UNUSED_PAD src0_sel:DWORD src1_sel:BYTE_0
	v_readlane_b32 s0, v254, 14
	v_and_b32_e32 v3, 32, v3
	v_bfe_i32 v14, v1, 0, 16
	v_readlane_b32 s1, v254, 15
	s_add_u32 s18, s25, s0
	v_add_lshl_u32 v1, v3, v14, 1
	s_addc_u32 s19, s26, s1
	s_add_i32 s28, s27, 0
	v_lshl_add_u32 v144, v2, 11, v1
	s_add_i32 m0, s28, 0x10000
	v_readlane_b32 s0, v254, 12
	global_load_lds_dwordx4 v144, s[18:19]
	s_add_i32 m0, s28, 0x12000
	v_readlane_b32 s1, v254, 13
	s_add_u32 s16, s23, s0
	v_lshl_add_u32 v132, v0, 11, v1
	global_load_lds_dwordx4 v128, s[18:19]
	s_addc_u32 s17, s24, s1
	s_mov_b32 m0, s28
	s_add_i32 s29, s28, 0x2000
	global_load_lds_dwordx4 v132, s[16:17]
	s_mov_b32 m0, s29
	s_add_u32 s6, s18, 0x40000
	global_load_lds_dwordx4 v130, s[16:17]
	s_addc_u32 s7, s19, 0
	s_add_i32 m0, s28, 0x14000
	v_mov_b32_e32 v129, v145
	global_load_lds_dwordx4 v144, s[6:7]
	s_add_i32 m0, s28, 0x16000
	v_mov_b32_e32 v133, v145
	global_load_lds_dwordx4 v128, s[6:7]
	s_add_u32 s6, s16, 0x40000
	s_addc_u32 s7, s17, 0
	s_add_i32 s30, s28, 0x4000
	s_mov_b32 m0, s30
	s_add_i32 s31, s28, 0x6000
	global_load_lds_dwordx4 v132, s[6:7]
	s_mov_b32 m0, s31
	v_mov_b32_e32 v131, v145
	global_load_lds_dwordx4 v130, s[6:7]
	v_lshl_add_u64 v[6:7], s[18:19], 0, v[144:145]
	v_lshl_add_u64 v[4:5], s[18:19], 0, v[128:129]
	v_lshl_add_u64 v[2:3], s[16:17], 0, v[132:133]
	s_cmp_lg_u32 s8, 1
	v_lshl_add_u64 v[0:1], s[16:17], 0, v[130:131]
	s_cbranch_scc1 .LBB0_150
	s_setprio 2
	s_barrier

.LBB0_1025:
	s_or_b64 exec, exec, s[6:7]
	v_readlane_b32 s0, v255, 7
	s_mov_b64 s[6:7], s[70:71]
	v_mov_b32_e32 v8, v226
	v_readlane_b32 s1, v255, 8
	s_waitcnt lgkmcnt(0)
	s_barrier
	s_and_b64 vcc, exec, s[0:1]
	v_readfirstlane_b32 s24, v8
	s_cbranch_vccnz .LBB0_1041
	v_lshlrev_b32_e32 v0, 4, v8
	v_add_u32_e32 v1, 0x2000, v0
	v_ashrrev_i32_e32 v2, 31, v1
	v_lshrrev_b32_e32 v2, 22, v2
	v_add_u32_e32 v2, v1, v2
	v_ashrrev_i32_e32 v9, 10, v2
	v_mul_i32_i24_e32 v3, 0x400, v9
	v_sub_u32_e32 v1, v1, v3
	v_lshrrev_b32_e32 v3, 4, v1
	v_bitop3_b32 v1, v3, v1, 32 bitop3:0x6c
	v_ashrrev_i32_e32 v3, 31, v1
	v_lshrrev_b32_e32 v3, 26, v3
	v_add_u32_e32 v3, v1, v3
	v_ashrrev_i32_e32 v10, 6, v3
	v_and_b32_e32 v3, 0xc0, v3
	v_sub_u32_e32 v1, v1, v3
	v_lshlrev_b32_e32 v2, 5, v9
	v_ashrrev_i16_sdwa v1, v230, sext(v1) dst_sel:DWORD dst_unused:UNUSED_PAD src0_sel:DWORD src1_sel:BYTE_0
	v_and_b32_e32 v2, 32, v2
	v_bfe_i32 v11, v1, 0, 16
	v_add_u32_e32 v1, v2, v11
	v_lshlrev_b32_e32 v2, 3, v9
	v_and_b32_e32 v2, 0x1ffff0, v2
	v_add_lshl_u32 v2, v10, v2, 11
	v_lshl_add_u32 v152, v1, 1, v2
	v_bfe_i32 v2, v8, 27, 1
	v_lshrrev_b32_e32 v2, 22, v2
	v_add_u32_e32 v2, v0, v2
	s_load_dwordx4 s[8:11], s[6:7], 0xb8
	s_load_dwordx2 s[4:5], s[6:7], 0x0
	v_and_b32_e32 v2, 0xfffffc00, v2
	v_sub_u32_e32 v0, v0, v2
	v_lshrrev_b32_e32 v2, 4, v0
	v_bitop3_b32 v2, v2, v0, 32 bitop3:0x6c
	v_ashrrev_i32_e32 v0, 31, v0
	v_lshrrev_b32_e32 v0, 26, v0
	s_waitcnt lgkmcnt(0)
	s_add_u32 s25, s10, 0x1abf0000
	v_ashrrev_i32_e32 v1, 31, v8
	v_add_u32_e32 v0, v2, v0
	s_addc_u32 s26, s11, 0
	v_readlane_b32 s0, v255, 1
	v_lshrrev_b32_e32 v1, 26, v1
	v_ashrrev_i32_e32 v13, 6, v0
	s_add_u32 s0, s10, s0
	v_add_u32_e32 v1, v8, v1
	v_mul_i32_i24_e32 v0, 64, v13
	s_addc_u32 s1, s11, 0
	v_ashrrev_i32_e32 v12, 6, v1
	v_sub_u32_e32 v0, v2, v0
	s_add_u32 s27, s0, 0x1380000
	v_lshlrev_b32_e32 v1, 5, v12
	v_ashrrev_i16_sdwa v0, v230, sext(v0) dst_sel:DWORD dst_unused:UNUSED_PAD src0_sel:DWORD src1_sel:BYTE_0
	s_addc_u32 s28, s1, 0
	s_ashr_i32 s12, s24, 6
	v_and_b32_e32 v1, 32, v1
	v_bfe_i32 v14, v0, 0, 16
	s_ashr_i32 s13, s24, 8
	s_lshl_b32 s29, s12, 10
	v_add_u32_e32 v0, v1, v14
	v_lshlrev_b32_e32 v1, 3, v12
	v_readlane_b32 s0, v254, 42
	v_and_b32_e32 v1, 0x1ffff0, v1
	v_readlane_b32 s1, v254, 43
	s_add_u32 s20, s27, s0
	v_add_lshl_u32 v1, v13, v1, 11
	s_addc_u32 s21, s28, s1
	s_add_i32 s30, s29, 0
	v_lshl_add_u32 v144, v0, 1, v1
	s_add_i32 m0, s30, 0x10000
	v_readlane_b32 s0, v254, 40
	global_load_lds_dwordx4 v144, s[20:21]
	s_add_i32 m0, s30, 0x12000
	v_readlane_b32 s1, v254, 41
	s_add_u32 s18, s25, s0
	global_load_lds_dwordx4 v152, s[20:21]
	s_addc_u32 s19, s26, s1
	s_mov_b32 m0, s30
	s_add_i32 s31, s30, 0x2000
	global_load_lds_dwordx4 v144, s[18:19]
	s_mov_b32 m0, s31
	s_add_u32 s0, s20, 0x40000
	global_load_lds_dwordx4 v152, s[18:19]
	s_addc_u32 s1, s21, 0
	s_add_i32 m0, s30, 0x14000
	v_mov_b32_e32 v153, v145
	global_load_lds_dwordx4 v144, s[0:1]
	s_add_i32 m0, s30, 0x16000
	v_lshl_add_u64 v[6:7], s[20:21], 0, v[144:145]
	global_load_lds_dwordx4 v152, s[0:1]
	s_add_u32 s0, s18, 0x40000
	s_addc_u32 s1, s19, 0
	s_add_i32 s34, s30, 0x4000
	s_mov_b32 m0, s34
	s_add_i32 s35, s30, 0x6000
	global_load_lds_dwordx4 v144, s[0:1]
	s_mov_b32 m0, s35
	v_lshl_add_u64 v[4:5], s[20:21], 0, v[152:153]
	global_load_lds_dwordx4 v152, s[0:1]
	v_lshl_add_u64 v[2:3], s[18:19], 0, v[144:145]
	s_cmp_lg_u32 s13, 1
	v_lshl_add_u64 v[0:1], s[18:19], 0, v[152:153]
	s_cbranch_scc1 .LBB0_1028
	s_setprio 2
	s_barrier
